# v102 + GEMM loop tile loads via SGPR base + 32-bit offset (24 64-bit adds per iteration set removed) + SwiGLU loop's first K-iteration peeled with zero srcC (no accumulator zeroing)
# baseline (speedup 1.0000x reference)
; DI const char* a_of(const Gemm& g, const Unit& u) { return (const char*)(g.A + (size_t)u.pz * g.zA + (size_t)u.pm * BM * g.lda); }
; DI const char* b_of(const Gemm& g, const Unit& u) { return (const char*)(g.Bt + (size_t)u.pz * g.zB + (size_t)u.pn * BM * g.ldb); }
; #define PG8_STAGE(bufoff, gbase, voff) do { _Pragma("unroll") for (int _i = 0; _i < 2; ++_i) \
;         __builtin_amdgcn_global_load_lds((const unsigned*)((const char*)(gbase) + (voff)[_i]), (LAS unsigned*)(lds + (bufoff) + ldsw + _i * 8192), 16, 0, 0); } while (0)
; #define PG8_WAIT_V(n) asm volatile("s_waitcnt vmcnt(" #n ")" ::: "memory")
; #define PG8_WAIT_L(n) asm volatile("s_waitcnt lgkmcnt(" #n ")" ::: "memory")
; template <class Epi>
; DI void gemm_phase(LAS unsigned char* lds, int tid, const Gemm g, const Order& S, const Epi& E) {
;     ...
;         const bool has_next = S.next(ui + 1, nxt);
;         const char* nA = has_next ? a_of(g, nxt) : cA; const char* nB = has_next ? b_of(g, nxt) : cB;
; #pragma unroll 1
;         for (int t = 0; t < nt; t += 2) {
;             const bool last = (t == nt - 2);
;             const char* a1 = cA + (size_t)(t + 1) * kstep;
;             const char* a2 = last ? nA : cA + (size_t)(t + 2) * kstep; const char* b2 = last ? nB : cB + (size_t)(t + 2) * kstep;
;             const char* a3 = a2 + kstep; const char* b3 = b2 + kstep;
;             PG8_LDB(B0, 0, 0); PG8_LDB(B1, 0, 1); PG8_SCHED; PG8_LDA(At, 0, 0); PG8_STAGE(PG8_SA(1, 1), a1 + hstepA, voffA);
;             PG8_WAIT_V(8); PG8_WAIT_L(0); PG8_BAR; PG8_MMA(0, 0, At, B0); PG8_MMA(0, 1, At, B1); PG8_BAR; PG8_SCHED;
;             PG8_LDA(At, 0, 1); PG8_STAGE(PG8_SB(0, 0), b2, voffB); PG8_STAGE(PG8_SB(0, 1), b2 + hstepB, voffB); PG8_STAGE(PG8_SA(0, 0), a2, voffA);
;             PG8_WAIT_V(8); PG8_WAIT_L(0); PG8_BAR; PG8_MMA(1, 0, At, B0); PG8_MMA(1, 1, At, B1); PG8_BAR; PG8_SCHED;
;             PG8_LDB(B0, 1, 0); PG8_LDB(B1, 1, 1); PG8_SCHED; PG8_LDA(At, 1, 0); PG8_STAGE(PG8_SA(0, 1), a2 + hstepA, voffA);
;             PG8_WAIT_V(8); PG8_WAIT_L(0); PG8_BAR; PG8_MMA(0, 0, At, B0); PG8_MMA(0, 1, At, B1); PG8_BAR; PG8_SCHED;
;             PG8_LDA(At, 1, 1); PG8_STAGE(PG8_SB(1, 0), b3, voffB); PG8_STAGE(PG8_SB(1, 1), b3 + hstepB, voffB); PG8_STAGE(PG8_SA(1, 0), a3, voffA);
;             PG8_WAIT_V(8); PG8_WAIT_L(0); PG8_BAR; PG8_MMA(1, 0, At, B0); PG8_MMA(1, 1, At, B1); PG8_BAR; PG8_SCHED;
.LBB0_512:
	s_ashr_i32 s67, s66, 31
	s_lshl_b64 s[40:41], s[66:67], 19
	s_add_u32 s68, s58, s40
	s_addc_u32 s69, s59, s41
	s_and_b64 s[40:41], s[4:5], exec
	s_cselect_b32 s39, s69, s75
	s_cselect_b32 s40, s68, s74
	s_ashr_i32 s65, s64, 31
	s_lshl_b64 s[46:47], s[64:65], 19
	s_add_u32 s70, s10, s46
	s_addc_u32 s71, s11, s47
	s_and_b64 s[46:47], s[4:5], exec
	s_cselect_b32 s41, s71, s77
	s_cselect_b32 s43, s70, s76
	s_add_u32 s74, s74, 0x40080
	s_addc_u32 s75, s75, 0
	s_add_u32 s45, s76, 0x100
	s_addc_u32 s46, s77, 0
	s_mov_b32 s47, -2
	s_add_u32 s48, s74, 0xfffc0080
	s_addc_u32 s49, s75, -1
	s_add_i32 s51, 0, 0x10000
	s_cmp_eq_u32 s47, 12
	s_cselect_b32 s79, s39, s49
	s_cselect_b32 s78, s40, s48
	s_cselect_b32 s77, s41, s46
	s_cselect_b32 s76, s43, s45
	s_add_i32 s52, 0, 0x14000
	v_add_u32_e32 v156, s51, v145
	v_add_u32_e32 v160, s52, v145
	ds_read_b128 v[140:143], v156
	ds_read_b128 v[148:151], v156 offset:1024
	ds_read_b128 v[152:155], v156 offset:2048
	ds_read_b128 v[156:159], v156 offset:3072
	ds_read_b128 v[164:167], v160
	ds_read_b128 v[170:173], v160 offset:1024
	ds_read_b128 v[174:177], v160 offset:2048
	ds_read_b128 v[196:199], v160 offset:3072
	s_add_i32 m0, s22, 0xc000
	ds_read_b128 v[200:203], v147
	ds_read_b128 v[204:207], v147 offset:1024
	ds_read_b128 v[208:211], v147 offset:2048
	ds_read_b128 v[212:215], v147 offset:3072
	ds_read_b128 v[216:219], v147 offset:4096
	ds_read_b128 v[220:223], v147 offset:5120
	ds_read_b128 v[224:227], v147 offset:6144
	ds_read_b128 v[228:231], v147 offset:7168
	global_load_lds_dwordx4 v136, s[74:75]
	s_add_i32 m0, s22, 0xe000
	s_nop 0
	global_load_lds_dwordx4 v138, s[74:75]
	s_waitcnt vmcnt(8)
	s_waitcnt lgkmcnt(0)
	s_barrier
	s_setprio 1
	s_waitcnt lgkmcnt(0)
	v_mfma_f32_16x16x32_bf16 v[126:129], v[140:143], v[200:203], 0
	v_mfma_f32_16x16x32_bf16 v[122:125], v[152:155], v[200:203], 0
	v_mfma_f32_16x16x32_bf16 v[110:113], v[140:143], v[208:211], 0
	v_mfma_f32_16x16x32_bf16 v[106:109], v[152:155], v[208:211], 0
	v_mfma_f32_16x16x32_bf16 v[94:97], v[140:143], v[216:219], 0
	v_mfma_f32_16x16x32_bf16 v[90:93], v[152:155], v[216:219], 0
	v_mfma_f32_16x16x32_bf16 v[78:81], v[140:143], v[224:227], 0
	v_mfma_f32_16x16x32_bf16 v[74:77], v[152:155], v[224:227], 0
	v_mfma_f32_16x16x32_bf16 v[126:129], v[148:151], v[204:207], v[126:129]
	v_mfma_f32_16x16x32_bf16 v[122:125], v[156:159], v[204:207], v[122:125]
	v_mfma_f32_16x16x32_bf16 v[110:113], v[148:151], v[212:215], v[110:113]
	v_mfma_f32_16x16x32_bf16 v[106:109], v[156:159], v[212:215], v[106:109]
	v_mfma_f32_16x16x32_bf16 v[94:97], v[148:151], v[220:223], v[94:97]
	v_mfma_f32_16x16x32_bf16 v[90:93], v[156:159], v[220:223], v[90:93]
	v_mfma_f32_16x16x32_bf16 v[78:81], v[148:151], v[228:231], v[78:81]
	v_mfma_f32_16x16x32_bf16 v[74:77], v[156:159], v[228:231], v[74:77]
	s_setprio 0
	s_setprio 1
	v_mfma_f32_16x16x32_bf16 v[118:121], v[164:167], v[200:203], 0
	v_mfma_f32_16x16x32_bf16 v[114:117], v[174:177], v[200:203], 0
	v_mfma_f32_16x16x32_bf16 v[102:105], v[164:167], v[208:211], 0
	v_mfma_f32_16x16x32_bf16 v[98:101], v[174:177], v[208:211], 0
	v_mfma_f32_16x16x32_bf16 v[86:89], v[164:167], v[216:219], 0
	v_mfma_f32_16x16x32_bf16 v[82:85], v[174:177], v[216:219], 0
	v_mfma_f32_16x16x32_bf16 v[70:73], v[164:167], v[224:227], 0
	v_mfma_f32_16x16x32_bf16 v[66:69], v[174:177], v[224:227], 0
	v_mfma_f32_16x16x32_bf16 v[118:121], v[170:173], v[204:207], v[118:121]
	v_mfma_f32_16x16x32_bf16 v[114:117], v[196:199], v[204:207], v[114:117]
	v_mfma_f32_16x16x32_bf16 v[102:105], v[170:173], v[212:215], v[102:105]
	v_mfma_f32_16x16x32_bf16 v[98:101], v[196:199], v[212:215], v[98:101]
	v_mfma_f32_16x16x32_bf16 v[86:89], v[170:173], v[220:223], v[86:89]
	v_mfma_f32_16x16x32_bf16 v[82:85], v[196:199], v[220:223], v[82:85]
	v_mfma_f32_16x16x32_bf16 v[70:73], v[170:173], v[228:231], v[70:73]
	v_mfma_f32_16x16x32_bf16 v[66:69], v[196:199], v[228:231], v[66:69]
	s_setprio 0
	s_barrier
	s_add_i32 s48, s51, s17
	v_lshl_add_u64 v[160:161], s[76:77], 0, v[0:1]
	s_mov_b32 m0, s48
	ds_read_b128 v[200:203], v147 offset:16384
	ds_read_b128 v[204:207], v147 offset:17408
	ds_read_b128 v[208:211], v147 offset:18432
	ds_read_b128 v[212:215], v147 offset:19456
	ds_read_b128 v[216:219], v147 offset:20480
	ds_read_b128 v[220:223], v147 offset:21504
	ds_read_b128 v[224:227], v147 offset:22528
	ds_read_b128 v[228:231], v147 offset:23552
	global_load_lds_dwordx4 v0, s[76:77]
	s_add_i32 m0, s48, 0x2000
	s_add_u32 s48, s76, 0x40000
	v_lshl_add_u64 v[178:179], s[76:77], 0, v[134:135]
	s_addc_u32 s49, s77, 0
	s_add_i32 s51, s52, s17
	global_load_lds_dwordx4 v134, s[76:77]
	s_mov_b32 m0, s51
	v_lshl_add_u64 v[190:191], s[78:79], 0, v[132:133]
	global_load_lds_dwordx4 v0, s[48:49]
	s_add_i32 m0, s51, 0x2000
	s_nop 0
	global_load_lds_dwordx4 v134, s[48:49]
	v_lshl_add_u64 v[188:189], s[78:79], 0, v[130:131]
	s_mov_b32 m0, s22
	s_nop 0
	global_load_lds_dwordx4 v130, s[78:79]
	s_mov_b32 m0, s26
	s_nop 0
	global_load_lds_dwordx4 v132, s[78:79]
	s_waitcnt vmcnt(8)
	s_waitcnt lgkmcnt(0)
	s_barrier
; #define PG8_STAGE(bufoff, gbase, voff) do { _Pragma("unroll") for (int _i = 0; _i < 2; ++_i) \
;         __builtin_amdgcn_global_load_lds((const unsigned*)((const char*)(gbase) + (voff)[_i]), (LAS unsigned*)(lds + (bufoff) + ldsw + _i * 8192), 16, 0, 0); } while (0)
; #define PG8_LDA(dst, b, h) do { _Pragma("unroll") for (int m = 0; m < 4; ++m) _Pragma("unroll") for (int k = 0; k < 2; ++k) dst[m][k] = *(const LAS bf16x8*)(lds + PG8_SA(b, h) + aoff + m * 2048 + k * 1024); } while (0)
; #define PG8_LDB(dst, b, h) do { _Pragma("unroll") for (int n = 0; n < 2; ++n) _Pragma("unroll") for (int k = 0; k < 2; ++k) dst[n][k] = *(const LAS bf16x8*)(lds + PG8_SB(b, h) + boff + n * 2048 + k * 1024); } while (0)
; #define PG8_MMA(ai, bj, At, Bt) do { __builtin_amdgcn_s_setprio(1); _Pragma("unroll") for (int m = 0; m < 4; ++m) _Pragma("unroll") for (int n = 0; n < 2; ++n) _Pragma("unroll") for (int k = 0; k < 2; ++k) \
;         acc[ai][bj][m][n] = __builtin_amdgcn_mfma_f32_16x16x32_bf16(Bt[n][k], At[m][k], acc[ai][bj][m][n], 0, 0, 0); __builtin_amdgcn_s_setprio(0); } while (0)
; #define PG8_WAIT_V(n) asm volatile("s_waitcnt vmcnt(" #n ")" ::: "memory")
; #define PG8_WAIT_L(n) asm volatile("s_waitcnt lgkmcnt(" #n ")" ::: "memory")
; template <class Epi>
; DI void gemm_phase(LAS unsigned char* lds, int tid, const Gemm g, const Order& S, const Epi& E) {
;     ...
;             PG8_LDB(B0, 0, 0); PG8_LDB(B1, 0, 1); PG8_SCHED; PG8_LDA(At, 0, 0); PG8_STAGE(PG8_SA(1, 1), a1 + hstepA, voffA);
;             PG8_WAIT_V(8); PG8_WAIT_L(0); PG8_BAR; PG8_MMA(0, 0, At, B0); PG8_MMA(0, 1, At, B1); PG8_BAR; PG8_SCHED;
;             PG8_LDA(At, 0, 1); PG8_STAGE(PG8_SB(0, 0), b2, voffB); PG8_STAGE(PG8_SB(0, 1), b2 + hstepB, voffB); PG8_STAGE(PG8_SA(0, 0), a2, voffA);
;             PG8_WAIT_V(8); PG8_WAIT_L(0); PG8_BAR; PG8_MMA(1, 0, At, B0); PG8_MMA(1, 1, At, B1); PG8_BAR; PG8_SCHED;
;             PG8_LDB(B0, 1, 0); PG8_LDB(B1, 1, 1); PG8_SCHED; PG8_LDA(At, 1, 0); PG8_STAGE(PG8_SA(0, 1), a2 + hstepA, voffA);
;             PG8_WAIT_V(8); PG8_WAIT_L(0); PG8_BAR; PG8_MMA(0, 0, At, B0); PG8_MMA(0, 1, At, B1); PG8_BAR; PG8_SCHED;
;             PG8_LDA(At, 1, 1); PG8_STAGE(PG8_SB(1, 0), b3, voffB); PG8_STAGE(PG8_SB(1, 1), b3 + hstepB, voffB); PG8_STAGE(PG8_SA(1, 0), a3, voffA);
;             PG8_WAIT_V(8); PG8_WAIT_L(0); PG8_BAR; PG8_MMA(1, 0, At, B0); PG8_MMA(1, 1, At, B1); PG8_BAR; PG8_SCHED;
	s_setprio 1
	s_waitcnt lgkmcnt(0)
	v_mfma_f32_16x16x32_bf16 v[62:65], v[140:143], v[200:203], 0
	v_mfma_f32_16x16x32_bf16 v[58:61], v[152:155], v[200:203], 0
	v_mfma_f32_16x16x32_bf16 v[46:49], v[140:143], v[208:211], 0
	v_mfma_f32_16x16x32_bf16 v[42:45], v[152:155], v[208:211], 0
	v_mfma_f32_16x16x32_bf16 v[30:33], v[140:143], v[216:219], 0
	v_mfma_f32_16x16x32_bf16 v[26:29], v[152:155], v[216:219], 0
	v_mfma_f32_16x16x32_bf16 v[14:17], v[140:143], v[224:227], 0
	v_mfma_f32_16x16x32_bf16 v[10:13], v[152:155], v[224:227], 0
	v_mfma_f32_16x16x32_bf16 v[62:65], v[148:151], v[204:207], v[62:65]
	v_mfma_f32_16x16x32_bf16 v[58:61], v[156:159], v[204:207], v[58:61]
	v_mfma_f32_16x16x32_bf16 v[46:49], v[148:151], v[212:215], v[46:49]
	v_mfma_f32_16x16x32_bf16 v[42:45], v[156:159], v[212:215], v[42:45]
	v_mfma_f32_16x16x32_bf16 v[30:33], v[148:151], v[220:223], v[30:33]
	v_mfma_f32_16x16x32_bf16 v[26:29], v[156:159], v[220:223], v[26:29]
	v_mfma_f32_16x16x32_bf16 v[14:17], v[148:151], v[228:231], v[14:17]
	v_mfma_f32_16x16x32_bf16 v[10:13], v[156:159], v[228:231], v[10:13]
	s_setprio 0
	s_setprio 1
	v_mfma_f32_16x16x32_bf16 v[54:57], v[164:167], v[200:203], 0
	v_mfma_f32_16x16x32_bf16 v[50:53], v[174:177], v[200:203], 0
	v_mfma_f32_16x16x32_bf16 v[38:41], v[164:167], v[208:211], 0
	v_mfma_f32_16x16x32_bf16 v[34:37], v[174:177], v[208:211], 0
	v_mfma_f32_16x16x32_bf16 v[22:25], v[164:167], v[216:219], 0
	v_mfma_f32_16x16x32_bf16 v[18:21], v[174:177], v[216:219], 0
	v_mfma_f32_16x16x32_bf16 v[6:9], v[164:167], v[224:227], 0
	v_mfma_f32_16x16x32_bf16 v[2:5], v[174:177], v[224:227], 0
	v_mfma_f32_16x16x32_bf16 v[54:57], v[170:173], v[204:207], v[54:57]
	v_mfma_f32_16x16x32_bf16 v[50:53], v[196:199], v[204:207], v[50:53]
	v_mfma_f32_16x16x32_bf16 v[38:41], v[170:173], v[212:215], v[38:41]
	v_mfma_f32_16x16x32_bf16 v[34:37], v[196:199], v[212:215], v[34:37]
	v_mfma_f32_16x16x32_bf16 v[22:25], v[170:173], v[220:223], v[22:25]
	v_mfma_f32_16x16x32_bf16 v[18:21], v[196:199], v[220:223], v[18:21]
	v_mfma_f32_16x16x32_bf16 v[6:9], v[170:173], v[228:231], v[6:9]
	v_mfma_f32_16x16x32_bf16 v[2:5], v[196:199], v[228:231], v[2:5]
	s_setprio 0
	s_barrier
	s_add_i32 s51, 0, 0x18000
	s_add_i32 s52, 0, 0x1c000
	v_add_u32_e32 v156, s51, v145
	v_add_u32_e32 v168, s52, v145
	ds_read_b128 v[140:143], v156
	ds_read_b128 v[148:151], v156 offset:1024
	ds_read_b128 v[152:155], v156 offset:2048
	ds_read_b128 v[156:159], v156 offset:3072
	ds_read_b128 v[164:167], v168
	ds_read_b128 v[170:173], v168 offset:1024
	ds_read_b128 v[174:177], v168 offset:2048
	ds_read_b128 v[196:199], v168 offset:3072
	s_add_u32 s48, s78, 0x40000
	s_addc_u32 s49, s79, 0
	s_mov_b32 m0, s28
	ds_read_b128 v[200:203], v147 offset:32768
	ds_read_b128 v[204:207], v147 offset:33792
	ds_read_b128 v[208:211], v147 offset:34816
	ds_read_b128 v[212:215], v147 offset:35840
	ds_read_b128 v[216:219], v147 offset:36864
	ds_read_b128 v[220:223], v147 offset:37888
	ds_read_b128 v[224:227], v147 offset:38912
	ds_read_b128 v[228:231], v147 offset:39936
	global_load_lds_dwordx4 v130, s[48:49]
	s_mov_b32 m0, s30
	s_nop 0
	global_load_lds_dwordx4 v132, s[48:49]
	s_waitcnt vmcnt(8)
	s_waitcnt lgkmcnt(0)
	s_barrier
	s_setprio 1
	s_waitcnt lgkmcnt(0)
	v_mfma_f32_16x16x32_bf16 v[126:129], v[140:143], v[200:203], v[126:129]
	v_mfma_f32_16x16x32_bf16 v[122:125], v[152:155], v[200:203], v[122:125]
	v_mfma_f32_16x16x32_bf16 v[110:113], v[140:143], v[208:211], v[110:113]
	v_mfma_f32_16x16x32_bf16 v[106:109], v[152:155], v[208:211], v[106:109]
	v_mfma_f32_16x16x32_bf16 v[94:97], v[140:143], v[216:219], v[94:97]
	v_mfma_f32_16x16x32_bf16 v[90:93], v[152:155], v[216:219], v[90:93]
	v_mfma_f32_16x16x32_bf16 v[78:81], v[140:143], v[224:227], v[78:81]
	v_mfma_f32_16x16x32_bf16 v[74:77], v[152:155], v[224:227], v[74:77]
	v_mfma_f32_16x16x32_bf16 v[126:129], v[148:151], v[204:207], v[126:129]
	v_mfma_f32_16x16x32_bf16 v[122:125], v[156:159], v[204:207], v[122:125]
	v_mfma_f32_16x16x32_bf16 v[110:113], v[148:151], v[212:215], v[110:113]
	v_mfma_f32_16x16x32_bf16 v[106:109], v[156:159], v[212:215], v[106:109]
	v_mfma_f32_16x16x32_bf16 v[94:97], v[148:151], v[220:223], v[94:97]
	v_mfma_f32_16x16x32_bf16 v[90:93], v[156:159], v[220:223], v[90:93]
	v_mfma_f32_16x16x32_bf16 v[78:81], v[148:151], v[228:231], v[78:81]
	v_mfma_f32_16x16x32_bf16 v[74:77], v[156:159], v[228:231], v[74:77]
	s_setprio 0
	s_setprio 1
	v_mfma_f32_16x16x32_bf16 v[118:121], v[164:167], v[200:203], v[118:121]
	v_mfma_f32_16x16x32_bf16 v[114:117], v[174:177], v[200:203], v[114:117]
	v_mfma_f32_16x16x32_bf16 v[102:105], v[164:167], v[208:211], v[102:105]
	v_mfma_f32_16x16x32_bf16 v[98:101], v[174:177], v[208:211], v[98:101]
	v_mfma_f32_16x16x32_bf16 v[86:89], v[164:167], v[216:219], v[86:89]
	v_mfma_f32_16x16x32_bf16 v[82:85], v[174:177], v[216:219], v[82:85]
	v_mfma_f32_16x16x32_bf16 v[70:73], v[164:167], v[224:227], v[70:73]
	v_mfma_f32_16x16x32_bf16 v[66:69], v[174:177], v[224:227], v[66:69]
	v_mfma_f32_16x16x32_bf16 v[118:121], v[170:173], v[204:207], v[118:121]
	v_mfma_f32_16x16x32_bf16 v[114:117], v[196:199], v[204:207], v[114:117]
	v_mfma_f32_16x16x32_bf16 v[102:105], v[170:173], v[212:215], v[102:105]
	v_mfma_f32_16x16x32_bf16 v[98:101], v[196:199], v[212:215], v[98:101]
	v_mfma_f32_16x16x32_bf16 v[86:89], v[170:173], v[220:223], v[86:89]
	v_mfma_f32_16x16x32_bf16 v[82:85], v[196:199], v[220:223], v[82:85]
	v_mfma_f32_16x16x32_bf16 v[70:73], v[170:173], v[228:231], v[70:73]
	v_mfma_f32_16x16x32_bf16 v[66:69], v[196:199], v[228:231], v[66:69]
	s_setprio 0
	s_barrier
; #define PG8_STAGE(bufoff, gbase, voff) do { _Pragma("unroll") for (int _i = 0; _i < 2; ++_i) \
;         __builtin_amdgcn_global_load_lds((const unsigned*)((const char*)(gbase) + (voff)[_i]), (LAS unsigned*)(lds + (bufoff) + ldsw + _i * 8192), 16, 0, 0); } while (0)
; #define PG8_LDA(dst, b, h) do { _Pragma("unroll") for (int m = 0; m < 4; ++m) _Pragma("unroll") for (int k = 0; k < 2; ++k) dst[m][k] = *(const LAS bf16x8*)(lds + PG8_SA(b, h) + aoff + m * 2048 + k * 1024); } while (0)
; #define PG8_LDB(dst, b, h) do { _Pragma("unroll") for (int n = 0; n < 2; ++n) _Pragma("unroll") for (int k = 0; k < 2; ++k) dst[n][k] = *(const LAS bf16x8*)(lds + PG8_SB(b, h) + boff + n * 2048 + k * 1024); } while (0)
; #define PG8_MMA(ai, bj, At, Bt) do { __builtin_amdgcn_s_setprio(1); _Pragma("unroll") for (int m = 0; m < 4; ++m) _Pragma("unroll") for (int n = 0; n < 2; ++n) _Pragma("unroll") for (int k = 0; k < 2; ++k) \
;         acc[ai][bj][m][n] = __builtin_amdgcn_mfma_f32_16x16x32_bf16(Bt[n][k], At[m][k], acc[ai][bj][m][n], 0, 0, 0); __builtin_amdgcn_s_setprio(0); } while (0)
; #define PG8_WAIT_V(n) asm volatile("s_waitcnt vmcnt(" #n ")" ::: "memory")
; #define PG8_WAIT_L(n) asm volatile("s_waitcnt lgkmcnt(" #n ")" ::: "memory")
; template <class Epi>
; DI void gemm_phase(LAS unsigned char* lds, int tid, const Gemm g, const Order& S, const Epi& E) {
;     ...
;         for (int t = 0; t < nt; t += 2) {
;             const bool last = (t == nt - 2);
;             const char* a1 = cA + (size_t)(t + 1) * kstep;
;             const char* a2 = last ? nA : cA + (size_t)(t + 2) * kstep; const char* b2 = last ? nB : cB + (size_t)(t + 2) * kstep;
;             const char* a3 = a2 + kstep; const char* b3 = b2 + kstep;
;             PG8_LDB(B0, 0, 0); PG8_LDB(B1, 0, 1); PG8_SCHED; PG8_LDA(At, 0, 0); PG8_STAGE(PG8_SA(1, 1), a1 + hstepA, voffA);
;     ...
;             PG8_LDB(B0, 1, 0); PG8_LDB(B1, 1, 1); PG8_SCHED; PG8_LDA(At, 1, 0); PG8_STAGE(PG8_SA(0, 1), a2 + hstepA, voffA);
;             PG8_WAIT_V(8); PG8_WAIT_L(0); PG8_BAR; PG8_MMA(0, 0, At, B0); PG8_MMA(0, 1, At, B1); PG8_BAR; PG8_SCHED;
;             PG8_LDA(At, 1, 1); PG8_STAGE(PG8_SB(1, 0), b3, voffB); PG8_STAGE(PG8_SB(1, 1), b3 + hstepB, voffB); PG8_STAGE(PG8_SA(1, 0), a3, voffA);
;             PG8_WAIT_V(8); PG8_WAIT_L(0); PG8_BAR; PG8_MMA(1, 0, At, B0); PG8_MMA(1, 1, At, B1); PG8_BAR; PG8_SCHED;
;         }
	s_add_i32 s48, s51, s17
	v_lshl_add_u64 v[160:161], v[160:161], 0, s[24:25]
	s_mov_b32 m0, s48
	ds_read_b128 v[200:203], v147 offset:49152
	ds_read_b128 v[204:207], v147 offset:50176
	ds_read_b128 v[208:211], v147 offset:51200
	ds_read_b128 v[212:215], v147 offset:52224
	ds_read_b128 v[216:219], v147 offset:53248
	ds_read_b128 v[220:223], v147 offset:54272
	ds_read_b128 v[224:227], v147 offset:55296
	ds_read_b128 v[228:231], v147 offset:56320
	global_load_lds_dwordx4 v[160:161], off
	s_add_i32 m0, s48, 0x2000
	s_add_u32 s48, s76, 0x40080
	v_lshl_add_u64 v[160:161], v[178:179], 0, s[24:25]
	s_addc_u32 s49, s77, 0
	s_add_i32 s51, s52, s17
	global_load_lds_dwordx4 v[160:161], off
	s_mov_b32 m0, s51
	s_nop 0
	global_load_lds_dwordx4 v0, s[48:49]
	s_add_i32 m0, s51, 0x2000
	s_nop 0
	global_load_lds_dwordx4 v134, s[48:49]
	v_lshl_add_u64 v[160:161], v[188:189], 0, s[24:25]
	s_mov_b32 m0, s34
	s_nop 0
	global_load_lds_dwordx4 v[160:161], off
	v_lshl_add_u64 v[160:161], v[190:191], 0, s[24:25]
	s_mov_b32 m0, s36
	s_nop 0
	global_load_lds_dwordx4 v[160:161], off
	s_waitcnt vmcnt(8)
	s_waitcnt lgkmcnt(0)
	s_barrier
	s_setprio 1
	s_waitcnt lgkmcnt(0)
	v_mfma_f32_16x16x32_bf16 v[62:65], v[140:143], v[200:203], v[62:65]
	v_mfma_f32_16x16x32_bf16 v[58:61], v[152:155], v[200:203], v[58:61]
	v_mfma_f32_16x16x32_bf16 v[46:49], v[140:143], v[208:211], v[46:49]
	v_mfma_f32_16x16x32_bf16 v[42:45], v[152:155], v[208:211], v[42:45]
	v_mfma_f32_16x16x32_bf16 v[30:33], v[140:143], v[216:219], v[30:33]
	v_mfma_f32_16x16x32_bf16 v[26:29], v[152:155], v[216:219], v[26:29]
	v_mfma_f32_16x16x32_bf16 v[14:17], v[140:143], v[224:227], v[14:17]
	v_mfma_f32_16x16x32_bf16 v[10:13], v[152:155], v[224:227], v[10:13]
	v_mfma_f32_16x16x32_bf16 v[62:65], v[148:151], v[204:207], v[62:65]
	v_mfma_f32_16x16x32_bf16 v[58:61], v[156:159], v[204:207], v[58:61]
	v_mfma_f32_16x16x32_bf16 v[46:49], v[148:151], v[212:215], v[46:49]
	v_mfma_f32_16x16x32_bf16 v[42:45], v[156:159], v[212:215], v[42:45]
	v_mfma_f32_16x16x32_bf16 v[30:33], v[148:151], v[220:223], v[30:33]
	v_mfma_f32_16x16x32_bf16 v[26:29], v[156:159], v[220:223], v[26:29]
	v_mfma_f32_16x16x32_bf16 v[14:17], v[148:151], v[228:231], v[14:17]
	v_mfma_f32_16x16x32_bf16 v[10:13], v[156:159], v[228:231], v[10:13]
	s_setprio 0
	s_setprio 1
	v_mfma_f32_16x16x32_bf16 v[54:57], v[164:167], v[200:203], v[54:57]
	v_mfma_f32_16x16x32_bf16 v[50:53], v[174:177], v[200:203], v[50:53]
	v_mfma_f32_16x16x32_bf16 v[38:41], v[164:167], v[208:211], v[38:41]
	v_mfma_f32_16x16x32_bf16 v[34:37], v[174:177], v[208:211], v[34:37]
	v_mfma_f32_16x16x32_bf16 v[22:25], v[164:167], v[216:219], v[22:25]
	v_mfma_f32_16x16x32_bf16 v[18:21], v[174:177], v[216:219], v[18:21]
	v_mfma_f32_16x16x32_bf16 v[6:9], v[164:167], v[224:227], v[6:9]
	v_mfma_f32_16x16x32_bf16 v[2:5], v[174:177], v[224:227], v[2:5]
	v_mfma_f32_16x16x32_bf16 v[54:57], v[170:173], v[204:207], v[54:57]
	v_mfma_f32_16x16x32_bf16 v[50:53], v[196:199], v[204:207], v[50:53]
	v_mfma_f32_16x16x32_bf16 v[38:41], v[170:173], v[212:215], v[38:41]
	v_mfma_f32_16x16x32_bf16 v[34:37], v[196:199], v[212:215], v[34:37]
	v_mfma_f32_16x16x32_bf16 v[22:25], v[170:173], v[220:223], v[22:25]
	v_mfma_f32_16x16x32_bf16 v[18:21], v[196:199], v[220:223], v[18:21]
	v_mfma_f32_16x16x32_bf16 v[6:9], v[170:173], v[228:231], v[6:9]
	v_mfma_f32_16x16x32_bf16 v[2:5], v[196:199], v[228:231], v[2:5]
	s_setprio 0
	s_barrier
	s_add_i32 s47, s47, 2
	s_add_u32 s74, s74, 0x100
	s_addc_u32 s75, s75, 0
	s_add_u32 s45, s45, 0x100
	s_addc_u32 s46, s46, 0
	s_cmp_gt_u32 s47, 13
	s_cbranch_scc1 .Lpeel_exit_513
.LBB0_513:
	s_add_u32 s48, s74, 0xfffc0080
	s_addc_u32 s49, s75, -1
	s_add_i32 s51, 0, 0x10000
	s_cmp_eq_u32 s47, 12
	s_cselect_b32 s79, s39, s49
	s_cselect_b32 s78, s40, s48
	s_cselect_b32 s77, s41, s46
	s_cselect_b32 s76, s43, s45
	s_add_i32 s52, 0, 0x14000
	v_add_u32_e32 v156, s51, v145
	v_add_u32_e32 v160, s52, v145
	ds_read_b128 v[140:143], v156
	ds_read_b128 v[148:151], v156 offset:1024
	ds_read_b128 v[152:155], v156 offset:2048
	ds_read_b128 v[156:159], v156 offset:3072
	ds_read_b128 v[164:167], v160
	ds_read_b128 v[170:173], v160 offset:1024
	ds_read_b128 v[174:177], v160 offset:2048
	ds_read_b128 v[196:199], v160 offset:3072
	s_add_i32 m0, s22, 0xc000
	ds_read_b128 v[200:203], v147
	ds_read_b128 v[204:207], v147 offset:1024
	ds_read_b128 v[208:211], v147 offset:2048
	ds_read_b128 v[212:215], v147 offset:3072
	ds_read_b128 v[216:219], v147 offset:4096
	ds_read_b128 v[220:223], v147 offset:5120
	ds_read_b128 v[224:227], v147 offset:6144
	ds_read_b128 v[228:231], v147 offset:7168
	global_load_lds_dwordx4 v136, s[74:75]
	s_add_i32 m0, s22, 0xe000
	s_nop 0
	global_load_lds_dwordx4 v138, s[74:75]
	s_waitcnt vmcnt(8)
	s_waitcnt lgkmcnt(0)
	s_barrier
; #define PG8_STAGE(bufoff, gbase, voff) do { _Pragma("unroll") for (int _i = 0; _i < 2; ++_i) \
;         __builtin_amdgcn_global_load_lds((const unsigned*)((const char*)(gbase) + (voff)[_i]), (LAS unsigned*)(lds + (bufoff) + ldsw + _i * 8192), 16, 0, 0); } while (0)
; #define PG8_LDA(dst, b, h) do { _Pragma("unroll") for (int m = 0; m < 4; ++m) _Pragma("unroll") for (int k = 0; k < 2; ++k) dst[m][k] = *(const LAS bf16x8*)(lds + PG8_SA(b, h) + aoff + m * 2048 + k * 1024); } while (0)
; #define PG8_LDB(dst, b, h) do { _Pragma("unroll") for (int n = 0; n < 2; ++n) _Pragma("unroll") for (int k = 0; k < 2; ++k) dst[n][k] = *(const LAS bf16x8*)(lds + PG8_SB(b, h) + boff + n * 2048 + k * 1024); } while (0)
; #define PG8_MMA(ai, bj, At, Bt) do { __builtin_amdgcn_s_setprio(1); _Pragma("unroll") for (int m = 0; m < 4; ++m) _Pragma("unroll") for (int n = 0; n < 2; ++n) _Pragma("unroll") for (int k = 0; k < 2; ++k) \
;         acc[ai][bj][m][n] = __builtin_amdgcn_mfma_f32_16x16x32_bf16(Bt[n][k], At[m][k], acc[ai][bj][m][n], 0, 0, 0); __builtin_amdgcn_s_setprio(0); } while (0)
; #define PG8_WAIT_V(n) asm volatile("s_waitcnt vmcnt(" #n ")" ::: "memory")
; #define PG8_WAIT_L(n) asm volatile("s_waitcnt lgkmcnt(" #n ")" ::: "memory")
; #define PG8_BAR __builtin_amdgcn_s_barrier()
; #define PG8_SCHED __builtin_amdgcn_sched_barrier(0)
; template <class Epi>
; DI void gemm_phase(LAS unsigned char* lds, int tid, const Gemm g, const Order& S, const Epi& E) {
;     ...
;             PG8_LDB(B0, 0, 0); PG8_LDB(B1, 0, 1); PG8_SCHED; PG8_LDA(At, 0, 0); PG8_STAGE(PG8_SA(1, 1), a1 + hstepA, voffA);
;             PG8_WAIT_V(8); PG8_WAIT_L(0); PG8_BAR; PG8_MMA(0, 0, At, B0); PG8_MMA(0, 1, At, B1); PG8_BAR; PG8_SCHED;
;             PG8_LDA(At, 0, 1); PG8_STAGE(PG8_SB(0, 0), b2, voffB); PG8_STAGE(PG8_SB(0, 1), b2 + hstepB, voffB); PG8_STAGE(PG8_SA(0, 0), a2, voffA);
;             PG8_WAIT_V(8); PG8_WAIT_L(0); PG8_BAR; PG8_MMA(1, 0, At, B0); PG8_MMA(1, 1, At, B1); PG8_BAR; PG8_SCHED;
;             PG8_LDB(B0, 1, 0); PG8_LDB(B1, 1, 1); PG8_SCHED; PG8_LDA(At, 1, 0); PG8_STAGE(PG8_SA(0, 1), a2 + hstepA, voffA);
;             PG8_WAIT_V(8); PG8_WAIT_L(0); PG8_BAR; PG8_MMA(0, 0, At, B0); PG8_MMA(0, 1, At, B1); PG8_BAR; PG8_SCHED;
	s_setprio 1
	s_waitcnt lgkmcnt(0)
	v_mfma_f32_16x16x32_bf16 v[126:129], v[140:143], v[200:203], v[126:129]
	v_mfma_f32_16x16x32_bf16 v[122:125], v[152:155], v[200:203], v[122:125]
	v_mfma_f32_16x16x32_bf16 v[110:113], v[140:143], v[208:211], v[110:113]
	v_mfma_f32_16x16x32_bf16 v[106:109], v[152:155], v[208:211], v[106:109]
	v_mfma_f32_16x16x32_bf16 v[94:97], v[140:143], v[216:219], v[94:97]
	v_mfma_f32_16x16x32_bf16 v[90:93], v[152:155], v[216:219], v[90:93]
	v_mfma_f32_16x16x32_bf16 v[78:81], v[140:143], v[224:227], v[78:81]
	v_mfma_f32_16x16x32_bf16 v[74:77], v[152:155], v[224:227], v[74:77]
	v_mfma_f32_16x16x32_bf16 v[126:129], v[148:151], v[204:207], v[126:129]
	v_mfma_f32_16x16x32_bf16 v[122:125], v[156:159], v[204:207], v[122:125]
	v_mfma_f32_16x16x32_bf16 v[110:113], v[148:151], v[212:215], v[110:113]
	v_mfma_f32_16x16x32_bf16 v[106:109], v[156:159], v[212:215], v[106:109]
	v_mfma_f32_16x16x32_bf16 v[94:97], v[148:151], v[220:223], v[94:97]
	v_mfma_f32_16x16x32_bf16 v[90:93], v[156:159], v[220:223], v[90:93]
	v_mfma_f32_16x16x32_bf16 v[78:81], v[148:151], v[228:231], v[78:81]
	v_mfma_f32_16x16x32_bf16 v[74:77], v[156:159], v[228:231], v[74:77]
	s_setprio 0
	s_setprio 1
	v_mfma_f32_16x16x32_bf16 v[118:121], v[164:167], v[200:203], v[118:121]
	v_mfma_f32_16x16x32_bf16 v[114:117], v[174:177], v[200:203], v[114:117]
	v_mfma_f32_16x16x32_bf16 v[102:105], v[164:167], v[208:211], v[102:105]
	v_mfma_f32_16x16x32_bf16 v[98:101], v[174:177], v[208:211], v[98:101]
	v_mfma_f32_16x16x32_bf16 v[86:89], v[164:167], v[216:219], v[86:89]
	v_mfma_f32_16x16x32_bf16 v[82:85], v[174:177], v[216:219], v[82:85]
	v_mfma_f32_16x16x32_bf16 v[70:73], v[164:167], v[224:227], v[70:73]
	v_mfma_f32_16x16x32_bf16 v[66:69], v[174:177], v[224:227], v[66:69]
	v_mfma_f32_16x16x32_bf16 v[118:121], v[170:173], v[204:207], v[118:121]
	v_mfma_f32_16x16x32_bf16 v[114:117], v[196:199], v[204:207], v[114:117]
	v_mfma_f32_16x16x32_bf16 v[102:105], v[170:173], v[212:215], v[102:105]
	v_mfma_f32_16x16x32_bf16 v[98:101], v[196:199], v[212:215], v[98:101]
	v_mfma_f32_16x16x32_bf16 v[86:89], v[170:173], v[220:223], v[86:89]
	v_mfma_f32_16x16x32_bf16 v[82:85], v[196:199], v[220:223], v[82:85]
	v_mfma_f32_16x16x32_bf16 v[70:73], v[170:173], v[228:231], v[70:73]
	v_mfma_f32_16x16x32_bf16 v[66:69], v[196:199], v[228:231], v[66:69]
	s_setprio 0
	s_barrier
	s_add_i32 s48, s51, s17
	v_lshl_add_u64 v[160:161], s[76:77], 0, v[0:1]
	s_mov_b32 m0, s48
	ds_read_b128 v[200:203], v147 offset:16384
	ds_read_b128 v[204:207], v147 offset:17408
	ds_read_b128 v[208:211], v147 offset:18432
	ds_read_b128 v[212:215], v147 offset:19456
	ds_read_b128 v[216:219], v147 offset:20480
	ds_read_b128 v[220:223], v147 offset:21504
	ds_read_b128 v[224:227], v147 offset:22528
	ds_read_b128 v[228:231], v147 offset:23552
	global_load_lds_dwordx4 v0, s[76:77]
	s_add_i32 m0, s48, 0x2000
	s_add_u32 s48, s76, 0x40000
	v_lshl_add_u64 v[178:179], s[76:77], 0, v[134:135]
	s_addc_u32 s49, s77, 0
	s_add_i32 s51, s52, s17
	global_load_lds_dwordx4 v134, s[76:77]
	s_mov_b32 m0, s51
	v_lshl_add_u64 v[190:191], s[78:79], 0, v[132:133]
	global_load_lds_dwordx4 v0, s[48:49]
	s_add_i32 m0, s51, 0x2000
	s_nop 0
	global_load_lds_dwordx4 v134, s[48:49]
	v_lshl_add_u64 v[188:189], s[78:79], 0, v[130:131]
	s_mov_b32 m0, s22
	s_nop 0
	global_load_lds_dwordx4 v130, s[78:79]
	s_mov_b32 m0, s26
	s_nop 0
	global_load_lds_dwordx4 v132, s[78:79]
	s_waitcnt vmcnt(8)
	s_waitcnt lgkmcnt(0)
	s_barrier
	s_setprio 1
	s_waitcnt lgkmcnt(0)
	v_mfma_f32_16x16x32_bf16 v[62:65], v[140:143], v[200:203], v[62:65]
	v_mfma_f32_16x16x32_bf16 v[58:61], v[152:155], v[200:203], v[58:61]
	v_mfma_f32_16x16x32_bf16 v[46:49], v[140:143], v[208:211], v[46:49]
	v_mfma_f32_16x16x32_bf16 v[42:45], v[152:155], v[208:211], v[42:45]
	v_mfma_f32_16x16x32_bf16 v[30:33], v[140:143], v[216:219], v[30:33]
	v_mfma_f32_16x16x32_bf16 v[26:29], v[152:155], v[216:219], v[26:29]
	v_mfma_f32_16x16x32_bf16 v[14:17], v[140:143], v[224:227], v[14:17]
	v_mfma_f32_16x16x32_bf16 v[10:13], v[152:155], v[224:227], v[10:13]
	v_mfma_f32_16x16x32_bf16 v[62:65], v[148:151], v[204:207], v[62:65]
	v_mfma_f32_16x16x32_bf16 v[58:61], v[156:159], v[204:207], v[58:61]
	v_mfma_f32_16x16x32_bf16 v[46:49], v[148:151], v[212:215], v[46:49]
	v_mfma_f32_16x16x32_bf16 v[42:45], v[156:159], v[212:215], v[42:45]
	v_mfma_f32_16x16x32_bf16 v[30:33], v[148:151], v[220:223], v[30:33]
	v_mfma_f32_16x16x32_bf16 v[26:29], v[156:159], v[220:223], v[26:29]
	v_mfma_f32_16x16x32_bf16 v[14:17], v[148:151], v[228:231], v[14:17]
	v_mfma_f32_16x16x32_bf16 v[10:13], v[156:159], v[228:231], v[10:13]
	s_setprio 0
	s_setprio 1
	v_mfma_f32_16x16x32_bf16 v[54:57], v[164:167], v[200:203], v[54:57]
	v_mfma_f32_16x16x32_bf16 v[50:53], v[174:177], v[200:203], v[50:53]
	v_mfma_f32_16x16x32_bf16 v[38:41], v[164:167], v[208:211], v[38:41]
	v_mfma_f32_16x16x32_bf16 v[34:37], v[174:177], v[208:211], v[34:37]
	v_mfma_f32_16x16x32_bf16 v[22:25], v[164:167], v[216:219], v[22:25]
	v_mfma_f32_16x16x32_bf16 v[18:21], v[174:177], v[216:219], v[18:21]
	v_mfma_f32_16x16x32_bf16 v[6:9], v[164:167], v[224:227], v[6:9]
	v_mfma_f32_16x16x32_bf16 v[2:5], v[174:177], v[224:227], v[2:5]
	v_mfma_f32_16x16x32_bf16 v[54:57], v[170:173], v[204:207], v[54:57]
	v_mfma_f32_16x16x32_bf16 v[50:53], v[196:199], v[204:207], v[50:53]
	v_mfma_f32_16x16x32_bf16 v[38:41], v[170:173], v[212:215], v[38:41]
	v_mfma_f32_16x16x32_bf16 v[34:37], v[196:199], v[212:215], v[34:37]
	v_mfma_f32_16x16x32_bf16 v[22:25], v[170:173], v[220:223], v[22:25]
	v_mfma_f32_16x16x32_bf16 v[18:21], v[196:199], v[220:223], v[18:21]
	v_mfma_f32_16x16x32_bf16 v[6:9], v[170:173], v[228:231], v[6:9]
	v_mfma_f32_16x16x32_bf16 v[2:5], v[196:199], v[228:231], v[2:5]
	s_setprio 0
	s_barrier
; #define PG8_STAGE(bufoff, gbase, voff) do { _Pragma("unroll") for (int _i = 0; _i < 2; ++_i) \
;         __builtin_amdgcn_global_load_lds((const unsigned*)((const char*)(gbase) + (voff)[_i]), (LAS unsigned*)(lds + (bufoff) + ldsw + _i * 8192), 16, 0, 0); } while (0)
; #define PG8_LDA(dst, b, h) do { _Pragma("unroll") for (int m = 0; m < 4; ++m) _Pragma("unroll") for (int k = 0; k < 2; ++k) dst[m][k] = *(const LAS bf16x8*)(lds + PG8_SA(b, h) + aoff + m * 2048 + k * 1024); } while (0)
; #define PG8_LDB(dst, b, h) do { _Pragma("unroll") for (int n = 0; n < 2; ++n) _Pragma("unroll") for (int k = 0; k < 2; ++k) dst[n][k] = *(const LAS bf16x8*)(lds + PG8_SB(b, h) + boff + n * 2048 + k * 1024); } while (0)
; #define PG8_MMA(ai, bj, At, Bt) do { __builtin_amdgcn_s_setprio(1); _Pragma("unroll") for (int m = 0; m < 4; ++m) _Pragma("unroll") for (int n = 0; n < 2; ++n) _Pragma("unroll") for (int k = 0; k < 2; ++k) \
;         acc[ai][bj][m][n] = __builtin_amdgcn_mfma_f32_16x16x32_bf16(Bt[n][k], At[m][k], acc[ai][bj][m][n], 0, 0, 0); __builtin_amdgcn_s_setprio(0); } while (0)
; #define PG8_WAIT_V(n) asm volatile("s_waitcnt vmcnt(" #n ")" ::: "memory")
; #define PG8_WAIT_L(n) asm volatile("s_waitcnt lgkmcnt(" #n ")" ::: "memory")
; #define PG8_BAR __builtin_amdgcn_s_barrier()
; #define PG8_SCHED __builtin_amdgcn_sched_barrier(0)
; template <class Epi>
; DI void gemm_phase(LAS unsigned char* lds, int tid, const Gemm g, const Order& S, const Epi& E) {
;     ...
;             PG8_LDB(B0, 1, 0); PG8_LDB(B1, 1, 1); PG8_SCHED; PG8_LDA(At, 1, 0); PG8_STAGE(PG8_SA(0, 1), a2 + hstepA, voffA);
;             PG8_WAIT_V(8); PG8_WAIT_L(0); PG8_BAR; PG8_MMA(0, 0, At, B0); PG8_MMA(0, 1, At, B1); PG8_BAR; PG8_SCHED;
;             PG8_LDA(At, 1, 1); PG8_STAGE(PG8_SB(1, 0), b3, voffB); PG8_STAGE(PG8_SB(1, 1), b3 + hstepB, voffB); PG8_STAGE(PG8_SA(1, 0), a3, voffA);
;             PG8_WAIT_V(8); PG8_WAIT_L(0); PG8_BAR; PG8_MMA(1, 0, At, B0); PG8_MMA(1, 1, At, B1); PG8_BAR; PG8_SCHED;
;         }
;         if (wr == 0) PG8_BAR;
	s_add_i32 s51, 0, 0x18000
	s_add_i32 s52, 0, 0x1c000
	v_add_u32_e32 v156, s51, v145
	v_add_u32_e32 v168, s52, v145
	ds_read_b128 v[140:143], v156
	ds_read_b128 v[148:151], v156 offset:1024
	ds_read_b128 v[152:155], v156 offset:2048
	ds_read_b128 v[156:159], v156 offset:3072
	ds_read_b128 v[164:167], v168
	ds_read_b128 v[170:173], v168 offset:1024
	ds_read_b128 v[174:177], v168 offset:2048
	ds_read_b128 v[196:199], v168 offset:3072
	s_add_u32 s48, s78, 0x40000
	s_addc_u32 s49, s79, 0
	s_mov_b32 m0, s28
	ds_read_b128 v[200:203], v147 offset:32768
	ds_read_b128 v[204:207], v147 offset:33792
	ds_read_b128 v[208:211], v147 offset:34816
	ds_read_b128 v[212:215], v147 offset:35840
	ds_read_b128 v[216:219], v147 offset:36864
	ds_read_b128 v[220:223], v147 offset:37888
	ds_read_b128 v[224:227], v147 offset:38912
	ds_read_b128 v[228:231], v147 offset:39936
	global_load_lds_dwordx4 v130, s[48:49]
	s_mov_b32 m0, s30
	s_nop 0
	global_load_lds_dwordx4 v132, s[48:49]
	s_waitcnt vmcnt(8)
	s_waitcnt lgkmcnt(0)
	s_barrier
	s_setprio 1
	s_waitcnt lgkmcnt(0)
	v_mfma_f32_16x16x32_bf16 v[126:129], v[140:143], v[200:203], v[126:129]
	v_mfma_f32_16x16x32_bf16 v[122:125], v[152:155], v[200:203], v[122:125]
	v_mfma_f32_16x16x32_bf16 v[110:113], v[140:143], v[208:211], v[110:113]
	v_mfma_f32_16x16x32_bf16 v[106:109], v[152:155], v[208:211], v[106:109]
	v_mfma_f32_16x16x32_bf16 v[94:97], v[140:143], v[216:219], v[94:97]
	v_mfma_f32_16x16x32_bf16 v[90:93], v[152:155], v[216:219], v[90:93]
	v_mfma_f32_16x16x32_bf16 v[78:81], v[140:143], v[224:227], v[78:81]
	v_mfma_f32_16x16x32_bf16 v[74:77], v[152:155], v[224:227], v[74:77]
	v_mfma_f32_16x16x32_bf16 v[126:129], v[148:151], v[204:207], v[126:129]
	v_mfma_f32_16x16x32_bf16 v[122:125], v[156:159], v[204:207], v[122:125]
	v_mfma_f32_16x16x32_bf16 v[110:113], v[148:151], v[212:215], v[110:113]
	v_mfma_f32_16x16x32_bf16 v[106:109], v[156:159], v[212:215], v[106:109]
	v_mfma_f32_16x16x32_bf16 v[94:97], v[148:151], v[220:223], v[94:97]
	v_mfma_f32_16x16x32_bf16 v[90:93], v[156:159], v[220:223], v[90:93]
	v_mfma_f32_16x16x32_bf16 v[78:81], v[148:151], v[228:231], v[78:81]
	v_mfma_f32_16x16x32_bf16 v[74:77], v[156:159], v[228:231], v[74:77]
	s_setprio 0
	s_setprio 1
	v_mfma_f32_16x16x32_bf16 v[118:121], v[164:167], v[200:203], v[118:121]
	v_mfma_f32_16x16x32_bf16 v[114:117], v[174:177], v[200:203], v[114:117]
	v_mfma_f32_16x16x32_bf16 v[102:105], v[164:167], v[208:211], v[102:105]
	v_mfma_f32_16x16x32_bf16 v[98:101], v[174:177], v[208:211], v[98:101]
	v_mfma_f32_16x16x32_bf16 v[86:89], v[164:167], v[216:219], v[86:89]
	v_mfma_f32_16x16x32_bf16 v[82:85], v[174:177], v[216:219], v[82:85]
	v_mfma_f32_16x16x32_bf16 v[70:73], v[164:167], v[224:227], v[70:73]
	v_mfma_f32_16x16x32_bf16 v[66:69], v[174:177], v[224:227], v[66:69]
	v_mfma_f32_16x16x32_bf16 v[118:121], v[170:173], v[204:207], v[118:121]
	v_mfma_f32_16x16x32_bf16 v[114:117], v[196:199], v[204:207], v[114:117]
	v_mfma_f32_16x16x32_bf16 v[102:105], v[170:173], v[212:215], v[102:105]
	v_mfma_f32_16x16x32_bf16 v[98:101], v[196:199], v[212:215], v[98:101]
	v_mfma_f32_16x16x32_bf16 v[86:89], v[170:173], v[220:223], v[86:89]
	v_mfma_f32_16x16x32_bf16 v[82:85], v[196:199], v[220:223], v[82:85]
	v_mfma_f32_16x16x32_bf16 v[70:73], v[170:173], v[228:231], v[70:73]
	v_mfma_f32_16x16x32_bf16 v[66:69], v[196:199], v[228:231], v[66:69]
	s_setprio 0
	s_barrier
	s_add_i32 s48, s51, s17
	v_lshl_add_u64 v[160:161], v[160:161], 0, s[24:25]
	s_mov_b32 m0, s48
	ds_read_b128 v[200:203], v147 offset:49152
	ds_read_b128 v[204:207], v147 offset:50176
	ds_read_b128 v[208:211], v147 offset:51200
	ds_read_b128 v[212:215], v147 offset:52224
	ds_read_b128 v[216:219], v147 offset:53248
	ds_read_b128 v[220:223], v147 offset:54272
	ds_read_b128 v[224:227], v147 offset:55296
	ds_read_b128 v[228:231], v147 offset:56320
	global_load_lds_dwordx4 v[160:161], off
	s_add_i32 m0, s48, 0x2000
	s_add_u32 s48, s76, 0x40080
	v_lshl_add_u64 v[160:161], v[178:179], 0, s[24:25]
	s_addc_u32 s49, s77, 0
	s_add_i32 s51, s52, s17
	global_load_lds_dwordx4 v[160:161], off
	s_mov_b32 m0, s51
	s_nop 0
	global_load_lds_dwordx4 v0, s[48:49]
	s_add_i32 m0, s51, 0x2000
	s_nop 0
	global_load_lds_dwordx4 v134, s[48:49]
	v_lshl_add_u64 v[160:161], v[188:189], 0, s[24:25]
	s_mov_b32 m0, s34
	s_nop 0
	global_load_lds_dwordx4 v[160:161], off
	v_lshl_add_u64 v[160:161], v[190:191], 0, s[24:25]
	s_mov_b32 m0, s36
	s_nop 0
	global_load_lds_dwordx4 v[160:161], off
	s_waitcnt vmcnt(8)
	s_waitcnt lgkmcnt(0)
	s_barrier
	s_setprio 1
	s_waitcnt lgkmcnt(0)
	v_mfma_f32_16x16x32_bf16 v[62:65], v[140:143], v[200:203], v[62:65]
	v_mfma_f32_16x16x32_bf16 v[58:61], v[152:155], v[200:203], v[58:61]
	v_mfma_f32_16x16x32_bf16 v[46:49], v[140:143], v[208:211], v[46:49]
	v_mfma_f32_16x16x32_bf16 v[42:45], v[152:155], v[208:211], v[42:45]
	v_mfma_f32_16x16x32_bf16 v[30:33], v[140:143], v[216:219], v[30:33]
	v_mfma_f32_16x16x32_bf16 v[26:29], v[152:155], v[216:219], v[26:29]
	v_mfma_f32_16x16x32_bf16 v[14:17], v[140:143], v[224:227], v[14:17]
	v_mfma_f32_16x16x32_bf16 v[10:13], v[152:155], v[224:227], v[10:13]
	v_mfma_f32_16x16x32_bf16 v[62:65], v[148:151], v[204:207], v[62:65]
	v_mfma_f32_16x16x32_bf16 v[58:61], v[156:159], v[204:207], v[58:61]
	v_mfma_f32_16x16x32_bf16 v[46:49], v[148:151], v[212:215], v[46:49]
	v_mfma_f32_16x16x32_bf16 v[42:45], v[156:159], v[212:215], v[42:45]
	v_mfma_f32_16x16x32_bf16 v[30:33], v[148:151], v[220:223], v[30:33]
	v_mfma_f32_16x16x32_bf16 v[26:29], v[156:159], v[220:223], v[26:29]
	v_mfma_f32_16x16x32_bf16 v[14:17], v[148:151], v[228:231], v[14:17]
	v_mfma_f32_16x16x32_bf16 v[10:13], v[156:159], v[228:231], v[10:13]
	s_setprio 0
	s_setprio 1
	v_mfma_f32_16x16x32_bf16 v[54:57], v[164:167], v[200:203], v[54:57]
	v_mfma_f32_16x16x32_bf16 v[50:53], v[174:177], v[200:203], v[50:53]
	v_mfma_f32_16x16x32_bf16 v[38:41], v[164:167], v[208:211], v[38:41]
	v_mfma_f32_16x16x32_bf16 v[34:37], v[174:177], v[208:211], v[34:37]
	v_mfma_f32_16x16x32_bf16 v[22:25], v[164:167], v[216:219], v[22:25]
	v_mfma_f32_16x16x32_bf16 v[18:21], v[174:177], v[216:219], v[18:21]
	v_mfma_f32_16x16x32_bf16 v[6:9], v[164:167], v[224:227], v[6:9]
	v_mfma_f32_16x16x32_bf16 v[2:5], v[174:177], v[224:227], v[2:5]
	v_mfma_f32_16x16x32_bf16 v[54:57], v[170:173], v[204:207], v[54:57]
	v_mfma_f32_16x16x32_bf16 v[50:53], v[196:199], v[204:207], v[50:53]
	v_mfma_f32_16x16x32_bf16 v[38:41], v[170:173], v[212:215], v[38:41]
	v_mfma_f32_16x16x32_bf16 v[34:37], v[196:199], v[212:215], v[34:37]
	v_mfma_f32_16x16x32_bf16 v[22:25], v[170:173], v[220:223], v[22:25]
	v_mfma_f32_16x16x32_bf16 v[18:21], v[196:199], v[220:223], v[18:21]
	v_mfma_f32_16x16x32_bf16 v[6:9], v[170:173], v[228:231], v[6:9]
	v_mfma_f32_16x16x32_bf16 v[2:5], v[196:199], v[228:231], v[2:5]
	s_setprio 0
	s_barrier
	s_add_i32 s47, s47, 2
	s_add_u32 s74, s74, 0x100
	s_addc_u32 s75, s75, 0
	s_add_u32 s45, s45, 0x100
	s_addc_u32 s46, s46, 0
	s_cmp_gt_u32 s47, 13
	s_cbranch_scc0 .LBB0_513
.Lpeel_exit_513:
	s_and_b64 vcc, exec, s[8:9]
	s_cbranch_vccz .LBB0_516
	s_barrier
